# att1 plus early per-workgroup L2 write-back before arriving at the grid barrier
# baseline (speedup 1.0000x reference)
; __device__ __forceinline__ unsigned xb_add(unsigned* p, unsigned v) { return __hip_atomic_fetch_add(p, v, __ATOMIC_RELAXED, __HIP_MEMORY_SCOPE_AGENT); }
; __device__ __forceinline__ void xcd_barrier(const XcdBarrier& b) {
;     asm volatile("s_waitcnt vmcnt(0)" ::: "memory");
;     __syncthreads();
;     if (threadIdx.x == 0) {
;         unsigned* bar = b.bar;
;         __builtin_amdgcn_s_waitcnt(0);
;         unsigned nloc = b.st[0], nx = b.st[1];
;         if (nloc == 0u) { xcd_barrier_complete(bar, b.x, nloc, nx); b.st[0] = nloc; b.st[1] = nx; }
;         const unsigned old = xb_add(&bar[XB_XSUB(b.x)], 1u);
;         const unsigned gen = old / nloc;
;         if (old + 1u == (gen + 1u) * nloc) {
;             __builtin_amdgcn_fence(__ATOMIC_RELEASE, "agent");
.LBB1_733:
	s_cmp_eq_u32 s68, s56
	v_readlane_b32 s6, v252, 11
	s_cselect_b64 s[4:5], -1, 0
	v_readlane_b32 s7, v252, 12
	s_or_b64 s[4:5], s[6:7], s[4:5]
	s_andn2_b64 vcc, exec, s[4:5]
	s_mov_b64 s[4:5], -1
	s_cbranch_vccz .LBB1_783
	s_waitcnt vmcnt(0)
	s_waitcnt lgkmcnt(0)
	s_barrier
	s_mov_b64 s[4:5], exec
	v_readlane_b32 s6, v254, 29
	v_readlane_b32 s7, v254, 30
	s_and_b64 s[6:7], s[4:5], s[6:7]
	s_mov_b64 exec, s[6:7]
	s_cbranch_execz .LBB1_782
	buffer_wbl2 sc1
	v_readlane_b32 s6, v254, 27
	s_waitcnt vmcnt(0) expcnt(0) lgkmcnt(0)
	s_nop 0
	v_mov_b32_e32 v0, s6
	ds_read_b32 v3, v0
	v_readlane_b32 s6, v254, 28
	s_waitcnt lgkmcnt(0)
	v_cmp_ne_u32_e32 vcc, 0, v3
	v_mov_b32_e32 v0, s6
	ds_read_b32 v2, v0
	s_cbranch_vccnz .LBB1_750
	s_mov_b32 s14, 1
	s_branch .LBB1_738
